# IDX score loop: per-iteration wait counts only the K-tile loads (vmcnt(4)); the previous iteration's four score stores stay in flight; full drain in front of the loop
# baseline (speedup 1.0000x reference)
; #define LAS __attribute__((address_space(3)))
; __device__ __forceinline__ void idx_unit(bf16* QB, float* SC, int* SEL, const float* qg, const float* kg, int b, int tp, LAS unsigned char* wl, int lane, bool do_norm) {
;     ...
;     if (ce > 256) {
;         bf16x8 af[2][4];
; #pragma unroll
;         for (int q2 = 0; q2 < 2; ++q2) { const bf16* ap = QB + (row + 2 * q2 + (n >> 4)) * NBP + CQI + (n & 15) * 64 + 8 * hi;
; #pragma unroll
;           for (int ks = 0; ks < 4; ++ks) af[q2][ks] = *(const bf16x8*)(ap + 16 * ks); }
;         float w[4][8];
; #pragma unroll
;         for (int a = 0; a < 4; ++a)
; #pragma unroll
;             for (int r = 0; r < 8; ++r) { const int hh = (r & 3) + 8 * (r >> 2) + 4 * hi; w[a][r] = 0.25f * bflo((unsigned)QB[(row + a) * NBP + CWI + hh]); }
;         float* scw0 = SC + (row + hi) * SEQ + n; float* scw1 = scw0 + 2 * (size_t)SEQ;
;         const int r8 = lane >> 3, c8 = lane & 7;
;         const bf16* kg8 = QB + (rowbase + r8) * NBP + CKI + c8 * 8;
;         LAS unsigned char* sdst = wl + r8 * 144 + c8 * 16;
;         const LAS unsigned char* fsrc = wl + n * 144 + 16 * hi;
;         bf16x8 cur[8];
; #pragma unroll
;         for (int i = 0; i < 8; ++i) cur[i] = *(const bf16x8*)(kg8 + (size_t)(8 * i) * NBP);
.LBB0_241:
	s_and_b64 vcc, exec, s[4:5]
	v_writelane_b32 v250, s11, 33
	s_cbranch_vccz .LBB0_561
	v_readlane_b32 s8, v253, 53
	v_readlane_b32 s9, v253, 54
	v_or_b32_e32 v2, s2, v108
	s_movk_i32 s11, 0x2200
	v_mov_b64_e32 v[0:1], s[8:9]
	v_mad_u64_u32 v[2:3], s[4:5], v2, s11, v[0:1]
	v_mad_i32_i24 v3, s79, v212, v3
	v_lshl_add_u64 v[2:3], v[2:3], 0, v[182:183]
	v_lshl_add_u64 v[2:3], v[2:3], 0, v[128:129]
	s_mov_b64 s[12:13], 0x1800
	v_lshl_add_u64 v[4:5], v[2:3], 0, s[12:13]
	v_add_co_u32_e32 v2, vcc, 0x1000, v2
	v_lshl_add_u64 v[18:19], s[0:1], 0, v[114:115]
	s_nop 0
	v_addc_co_u32_e32 v3, vcc, 0, v3, vcc
	global_load_dwordx4 v[32:35], v[4:5], off offset:32
	global_load_dwordx4 v[36:39], v[4:5], off offset:64
	global_load_dwordx4 v[40:43], v[2:3], off offset:2048
	global_load_dwordx4 v[44:47], v[4:5], off offset:96
	v_or_b32_e32 v2, s2, v110
	v_mad_u64_u32 v[2:3], s[4:5], v2, s11, v[0:1]
	v_mad_i32_i24 v3, s79, v212, v3
	v_lshl_add_u64 v[2:3], v[2:3], 0, v[182:183]
	v_lshl_add_u64 v[2:3], v[2:3], 0, v[128:129]
	s_movk_i32 s4, 0x1000
	v_lshl_add_u64 v[4:5], v[2:3], 0, s[12:13]
	v_add_co_u32_e32 v2, vcc, s4, v2
	s_mul_i32 s4, s79, 0x2200
	s_mul_hi_u32 s5, s2, 0x2200
	s_add_i32 s5, s5, s4
	s_mul_i32 s4, s2, 0x2200
	s_add_u32 s4, s8, s4
	v_addc_co_u32_e32 v3, vcc, 0, v3, vcc
	s_addc_u32 s5, s9, s5
	global_load_dwordx4 v[48:51], v[4:5], off offset:32
	global_load_dwordx4 v[52:55], v[4:5], off offset:64
	global_load_dwordx4 v[56:59], v[2:3], off offset:2048
	global_load_dwordx4 v[60:63], v[4:5], off offset:96
	v_lshl_add_u64 v[2:3], v[112:113], 1, s[4:5]
	s_mov_b64 s[4:5], 0x2080
	v_lshl_add_u64 v[4:5], v[2:3], 0, s[4:5]
	v_add_co_u32_e32 v6, vcc, s10, v2
	s_mov_b64 s[4:5], 0x4280
	s_nop 0
	v_addc_co_u32_e32 v7, vcc, 0, v3, vcc
	v_lshl_add_u64 v[8:9], v[2:3], 0, s[4:5]
	s_movk_i32 s4, 0x4000
	v_add_co_u32_e32 v10, vcc, s4, v2
	s_mov_b64 s[4:5], 0x6480
	s_nop 0
	v_addc_co_u32_e32 v11, vcc, 0, v3, vcc
	global_load_dwordx2 v[6:7], v[6:7], off offset:128
	s_nop 0
	global_load_dwordx2 v[10:11], v[10:11], off offset:640
	s_nop 0
	global_load_dwordx2 v[8:9], v[8:9], off offset:16
	s_nop 0
	global_load_dwordx2 v[4:5], v[4:5], off offset:16
	v_lshl_add_u64 v[12:13], v[2:3], 0, s[4:5]
	s_movk_i32 s4, 0x6000
	v_add_co_u32_e32 v14, vcc, s4, v2
	s_mov_b64 s[4:5], 0x8680
	s_nop 0
	v_addc_co_u32_e32 v15, vcc, 0, v3, vcc
	v_lshl_add_u64 v[16:17], v[2:3], 0, s[4:5]
	s_mov_b32 s5, 0x8000
	v_mad_u64_u32 v[0:1], s[0:1], v18, s11, v[0:1]
	v_add_co_u32_e32 v2, vcc, s5, v2
	v_mad_i32_i24 v1, v19, s11, v1
	v_mov_b32_e32 v131, v183
	v_addc_co_u32_e32 v3, vcc, 0, v3, vcc
	v_lshl_add_u64 v[0:1], v[0:1], 0, v[130:131]
	s_mov_b32 s0, 0x79000
	global_load_dwordx2 v[14:15], v[14:15], off offset:1152
	s_nop 0
	global_load_dwordx2 v[2:3], v[2:3], off offset:1664
	s_nop 0
	global_load_dwordx2 v[16:17], v[16:17], off offset:16
	s_nop 0
	global_load_dwordx2 v[12:13], v[12:13], off offset:16
	v_add_co_u32_e32 v18, vcc, s0, v0
	s_mov_b32 s0, 0x68000
	s_nop 0
	v_addc_co_u32_e32 v19, vcc, 0, v1, vcc
	v_add_co_u32_e32 v20, vcc, s0, v0
	s_mov_b32 s0, 0x57000
	s_nop 0
	v_addc_co_u32_e32 v21, vcc, 0, v1, vcc
	global_load_dwordx4 v[92:95], v[18:19], off
	global_load_dwordx4 v[84:87], v[20:21], off
	v_add_co_u32_e32 v18, vcc, s0, v0
	s_mov_b32 s0, 0x46000
	s_nop 0
	v_addc_co_u32_e32 v19, vcc, 0, v1, vcc
	v_add_co_u32_e32 v20, vcc, s0, v0
	s_mov_b32 s0, 0
	s_nop 0
	v_addc_co_u32_e32 v21, vcc, 0, v1, vcc
	global_load_dwordx4 v[88:91], v[18:19], off
	global_load_dwordx4 v[76:79], v[20:21], off
	v_add_co_u32_e32 v18, vcc, 0x35000, v0
	v_lshl_add_u64 v[132:133], v[0:1], 0, s[14:15]
	s_nop 0
	v_addc_co_u32_e32 v19, vcc, 0, v1, vcc
	v_add_co_u32_e32 v20, vcc, 0x24000, v0
	s_nop 1
	v_addc_co_u32_e32 v21, vcc, 0, v1, vcc
	global_load_dwordx4 v[80:83], v[18:19], off
	global_load_dwordx4 v[68:71], v[20:21], off
	v_add_co_u32_e32 v18, vcc, 0x13000, v0
	s_nop 1
	v_addc_co_u32_e32 v19, vcc, 0, v1, vcc
	v_add_co_u32_e32 v20, vcc, 0x2000, v0
	s_nop 1
	v_addc_co_u32_e32 v21, vcc, 0, v1, vcc
	global_load_dwordx4 v[72:75], v[18:19], off
	global_load_dwordx4 v[64:67], v[20:21], off
	s_waitcnt vmcnt(15)
	v_lshlrev_b32_e32 v18, 16, v6
	v_and_b32_e32 v6, 0xffff0000, v6
	v_mul_f32_e32 v217, 0x3d000000, v6
	v_lshlrev_b32_e32 v6, 16, v7
	v_mul_f32_e32 v218, 0x3d000000, v6
	v_and_b32_e32 v6, 0xffff0000, v7
	v_mul_f32_e32 v219, 0x3d000000, v6
	s_waitcnt vmcnt(12)
	v_lshlrev_b32_e32 v6, 16, v4
	v_and_b32_e32 v4, 0xffff0000, v4
	v_mul_f32_e32 v221, 0x3d000000, v4
	v_lshlrev_b32_e32 v4, 16, v5
	v_mul_f32_e32 v222, 0x3d000000, v4
	v_and_b32_e32 v4, 0xffff0000, v5
	v_mul_f32_e32 v223, 0x3d000000, v4
	v_lshlrev_b32_e32 v4, 16, v10
	v_mul_f32_e32 v224, 0x3d000000, v4
	v_and_b32_e32 v4, 0xffff0000, v10
	v_mul_f32_e32 v225, 0x3d000000, v4
	v_lshlrev_b32_e32 v4, 16, v11
	v_mul_f32_e32 v226, 0x3d000000, v4
	v_and_b32_e32 v4, 0xffff0000, v11
	v_mul_f32_e32 v227, 0x3d000000, v4
	v_lshlrev_b32_e32 v4, 16, v8
	v_mul_f32_e32 v228, 0x3d000000, v4
	v_and_b32_e32 v4, 0xffff0000, v8
	v_mul_f32_e32 v229, 0x3d000000, v4
	v_lshlrev_b32_e32 v4, 16, v9
	v_mul_f32_e32 v230, 0x3d000000, v4
	v_and_b32_e32 v4, 0xffff0000, v9
	v_mul_f32_e32 v231, 0x3d000000, v4
	s_waitcnt vmcnt(11)
	v_lshlrev_b32_e32 v4, 16, v14
	v_mul_f32_e32 v232, 0x3d000000, v4
	v_and_b32_e32 v4, 0xffff0000, v14
	v_mul_f32_e32 v233, 0x3d000000, v4
	v_lshlrev_b32_e32 v4, 16, v15
	v_mul_f32_e32 v234, 0x3d000000, v4
	v_and_b32_e32 v4, 0xffff0000, v15
	v_mul_f32_e32 v235, 0x3d000000, v4
	s_waitcnt vmcnt(8)
	v_lshlrev_b32_e32 v4, 16, v12
	v_mul_f32_e32 v236, 0x3d000000, v4
	v_and_b32_e32 v4, 0xffff0000, v12
	v_mul_f32_e32 v237, 0x3d000000, v4
	v_lshlrev_b32_e32 v4, 16, v13
	v_mul_f32_e32 v238, 0x3d000000, v4
	v_and_b32_e32 v4, 0xffff0000, v13
	v_mul_f32_e32 v239, 0x3d000000, v4
	v_lshlrev_b32_e32 v4, 16, v2
	v_and_b32_e32 v2, 0xffff0000, v2
	v_mul_f32_e32 v241, 0x3d000000, v2
	v_lshlrev_b32_e32 v2, 16, v3
	v_mul_f32_e32 v242, 0x3d000000, v2
	v_and_b32_e32 v2, 0xffff0000, v3
	v_mul_f32_e32 v243, 0x3d000000, v2
	v_lshlrev_b32_e32 v2, 16, v16
	v_mul_f32_e32 v244, 0x3d000000, v2
	v_and_b32_e32 v2, 0xffff0000, v16
	v_mul_f32_e32 v245, 0x3d000000, v2
	v_lshlrev_b32_e32 v2, 16, v17
	v_mul_f32_e32 v246, 0x3d000000, v2
	v_and_b32_e32 v2, 0xffff0000, v17
	v_mul_f32_e32 v247, 0x3d000000, v2
	v_lshl_add_u64 v[2:3], s[2:3], 0, v[106:107]
	v_lshlrev_b64 v[2:3], 14, v[2:3]
	v_mul_f32_e32 v131, 0x3d000000, v18
	v_mul_f32_e32 v220, 0x3d000000, v6
	v_mul_f32_e32 v240, 0x3d000000, v4
	v_lshl_add_u64 v[134:135], v[126:127], 0, v[2:3]
	s_waitcnt vmcnt(0)
; #define LAS __attribute__((address_space(3)))
; #define LDS_WAIT() asm volatile("s_waitcnt lgkmcnt(0)" ::: "memory")
; __device__ __forceinline__ void idx_unit(bf16* QB, float* SC, int* SEL, const float* qg, const float* kg, int b, int tp, LAS unsigned char* wl, int lane, bool do_norm) {
;     ...
;         for (int s0 = 0; s0 < ce; s0 += 64) {
; #pragma unroll
;             for (int i = 0; i < 8; ++i) *(LAS bf16x8*)(sdst + (8 * i) * 144) = cur[i];
;             const int sn = (s0 + 64 < ce) ? s0 + 64 : 0;
; #pragma unroll
;             for (int i = 0; i < 8; ++i) cur[i] = *(const bf16x8*)(kg8 + (size_t)(sn + 8 * i) * NBP);
;             LDS_WAIT();
; #pragma unroll
;             for (int tt = 0; tt < 2; ++tt) {
;                 f32x16 acc0, acc1;
; #pragma unroll
;                 for (int r = 0; r < 16; ++r) { acc0[r] = 0.f; acc1[r] = 0.f; }
; #pragma unroll
;                 for (int ks = 0; ks < 4; ++ks) { const bf16x8 bfr = *(const LAS bf16x8*)(fsrc + tt * 32 * 144 + 32 * ks);
;                     acc0 = __builtin_amdgcn_mfma_f32_32x32x16_bf16(af[0][ks], bfr, acc0, 0, 0, 0); acc1 = __builtin_amdgcn_mfma_f32_32x32x16_bf16(af[1][ks], bfr, acc1, 0, 0, 0); }
;                 float pa = 0.f, pb = 0.f, pc = 0.f, pd = 0.f;
; #pragma unroll
;                 for (int r = 0; r < 8; ++r) { pa += w[0][r] * (__builtin_fmaxf(acc0[r], 0.f) * 0.125f); pb += w[1][r] * (__builtin_fmaxf(acc0[8 + r], 0.f) * 0.125f);
;                                               pc += w[2][r] * (__builtin_fmaxf(acc1[r], 0.f) * 0.125f); pd += w[3][r] * (__builtin_fmaxf(acc1[8 + r], 0.f) * 0.125f); }
;                 const float snd0 = hi ? pa : pb, snd1 = hi ? pc : pd; const float rcv0 = __shfl_xor(snd0, 32), rcv1 = __shfl_xor(snd1, 32);
;                 scw0[s0 + 32 * tt] = (hi ? pb : pa) + rcv0;
;                 scw1[s0 + 32 * tt] = (hi ? pd : pc) + rcv1;
.LBB0_243:
	s_add_i32 s3, s0, 64
	s_cmp_lt_i32 s0, s7
	s_cselect_b64 s[0:1], -1, 0
	s_and_b64 vcc, s[0:1], exec
	s_cselect_b32 s4, s3, 0
	v_mad_u64_u32 v[0:1], s[0:1], s4, v212, v[132:133]
	s_waitcnt vmcnt(4)
	ds_write_b128 v101, v[64:67]
	ds_write_b128 v101, v[72:75] offset:1152
	ds_write_b128 v101, v[68:71] offset:2304
	ds_write_b128 v101, v[80:83] offset:3456
	ds_write_b128 v101, v[76:79] offset:4608
	ds_write_b128 v101, v[88:91] offset:5760
	ds_write_b128 v101, v[84:87] offset:6912
	ds_write_b128 v101, v[92:95] offset:8064
	s_or_b32 s0, s4, 8
	global_load_dwordx4 v[64:67], v[0:1], off
	v_mad_u64_u32 v[0:1], s[0:1], s0, v212, v[132:133]
	s_or_b32 s0, s4, 16
	global_load_dwordx4 v[72:75], v[0:1], off
	v_mad_u64_u32 v[0:1], s[0:1], s0, v212, v[132:133]
	s_or_b32 s0, s4, 24
	global_load_dwordx4 v[68:71], v[0:1], off
	v_mad_u64_u32 v[0:1], s[0:1], s0, v212, v[132:133]
	s_or_b32 s0, s4, 32
	global_load_dwordx4 v[80:83], v[0:1], off
	v_mad_u64_u32 v[0:1], s[0:1], s0, v212, v[132:133]
	s_or_b32 s0, s4, 40
	global_load_dwordx4 v[76:79], v[0:1], off
	v_mad_u64_u32 v[0:1], s[0:1], s0, v212, v[132:133]
	s_or_b32 s0, s4, 48
	global_load_dwordx4 v[88:91], v[0:1], off
	v_mad_u64_u32 v[0:1], s[0:1], s0, v212, v[132:133]
	s_or_b32 s0, s4, 56
	global_load_dwordx4 v[84:87], v[0:1], off
	v_mad_u64_u32 v[0:1], s[0:1], s0, v212, v[132:133]
	global_load_dwordx4 v[92:95], v[0:1], off
	s_waitcnt lgkmcnt(0)
	ds_read_b128 v[138:141], v103
	ds_read_b128 v[142:145], v103 offset:32
	ds_read_b128 v[146:149], v103 offset:64
	ds_read_b128 v[150:153], v103 offset:96
	s_waitcnt lgkmcnt(3)
	v_mfma_f32_32x32x16_bf16 v[16:31], v[40:43], v[138:141], 0
	v_add_co_u32_e64 v136, s[0:1], s5, v134
	s_nop 1
	v_addc_co_u32_e64 v137, s[0:1], 0, v135, s[0:1]
	s_mov_b64 s[0:1], 0x100
	v_mfma_f32_32x32x16_bf16 v[0:15], v[56:59], v[138:141], 0
	s_waitcnt lgkmcnt(2)
	v_mfma_f32_32x32x16_bf16 v[0:15], v[48:51], v[142:145], v[0:15]
	v_mfma_f32_32x32x16_bf16 v[16:31], v[32:35], v[142:145], v[16:31]
	s_waitcnt lgkmcnt(1)
	v_mfma_f32_32x32x16_bf16 v[0:15], v[52:55], v[146:149], v[0:15]
	v_mfma_f32_32x32x16_bf16 v[16:31], v[36:39], v[146:149], v[16:31]
	s_waitcnt lgkmcnt(0)
	v_mfma_f32_32x32x16_bf16 v[0:15], v[60:63], v[150:153], v[0:15]
	v_mfma_f32_32x32x16_bf16 v[16:31], v[44:47], v[150:153], v[16:31]
	ds_read_b128 v[154:157], v103 offset:4608
	ds_read_b128 v[158:161], v103 offset:4640
	ds_read_b128 v[162:165], v103 offset:4672
	ds_read_b128 v[166:169], v103 offset:4704
	s_nop 10
	v_max_f32_e32 v0, 0, v0
	v_max_f32_e32 v1, 0, v1
	v_fma_f32 v0, v232, v0, 0
	v_max_f32_e32 v8, 0, v8
	v_fmac_f32_e32 v0, v233, v1
	v_max_f32_e32 v1, 0, v9
	v_max_f32_e32 v16, 0, v16
	v_fma_f32 v8, v240, v8, 0
	v_max_f32_e32 v17, 0, v17
	v_fmac_f32_e32 v8, v241, v1
	v_fma_f32 v16, v131, v16, 0
	v_max_f32_e32 v1, 0, v18
	v_max_f32_e32 v24, 0, v24
	v_fmac_f32_e32 v16, v217, v17
	v_max_f32_e32 v17, 0, v25
	v_fmac_f32_e32 v16, v218, v1
	v_fma_f32 v24, v224, v24, 0
	v_max_f32_e32 v1, 0, v26
	v_fmac_f32_e32 v24, v225, v17
	v_fmac_f32_e32 v24, v226, v1
	v_max_f32_e32 v1, 0, v2
	v_fmac_f32_e32 v0, v234, v1
	v_max_f32_e32 v1, 0, v10
	v_fmac_f32_e32 v8, v242, v1
	v_max_f32_e32 v1, 0, v19
	v_fmac_f32_e32 v16, v219, v1
	v_max_f32_e32 v1, 0, v27
	v_fmac_f32_e32 v24, v227, v1
	v_max_f32_e32 v1, 0, v3
	v_fmac_f32_e32 v0, v235, v1
	v_max_f32_e32 v1, 0, v11
	v_fmac_f32_e32 v8, v243, v1
	v_max_f32_e32 v1, 0, v20
	v_fmac_f32_e32 v16, v220, v1
	v_max_f32_e32 v1, 0, v28
	v_fmac_f32_e32 v24, v228, v1
	v_max_f32_e32 v1, 0, v4
	v_fmac_f32_e32 v0, v236, v1
	v_max_f32_e32 v1, 0, v12
	v_fmac_f32_e32 v8, v244, v1
	v_max_f32_e32 v1, 0, v21
	v_fmac_f32_e32 v16, v221, v1
	v_max_f32_e32 v1, 0, v29
	v_fmac_f32_e32 v24, v229, v1
	v_max_f32_e32 v1, 0, v5
	v_fmac_f32_e32 v0, v237, v1
	v_max_f32_e32 v1, 0, v13
	v_fmac_f32_e32 v8, v245, v1
	v_max_f32_e32 v1, 0, v22
	v_fmac_f32_e32 v16, v222, v1
	v_max_f32_e32 v1, 0, v30
	v_fmac_f32_e32 v24, v230, v1
	v_max_f32_e32 v1, 0, v6
	v_fmac_f32_e32 v0, v238, v1
	v_max_f32_e32 v1, 0, v14
	v_fmac_f32_e32 v8, v246, v1
	v_max_f32_e32 v1, 0, v23
	v_fmac_f32_e32 v16, v223, v1
	v_max_f32_e32 v1, 0, v31
	v_fmac_f32_e32 v24, v231, v1
	v_max_f32_e32 v1, 0, v7
	v_fmac_f32_e32 v0, v239, v1
	v_max_f32_e32 v1, 0, v15
	v_fmac_f32_e32 v8, v247, v1
	v_cndmask_b32_e64 v1, v16, v24, s[40:41]
	v_cndmask_b32_e64 v2, v0, v8, s[40:41]
	ds_bpermute_b32 v1, v97, v1
	ds_bpermute_b32 v2, v97, v2
	v_cndmask_b32_e64 v3, v24, v16, s[40:41]
	v_cndmask_b32_e64 v0, v8, v0, s[40:41]
	s_waitcnt lgkmcnt(1)
	v_add_f32_e32 v1, v3, v1
	s_waitcnt lgkmcnt(0)
; #define LAS __attribute__((address_space(3)))
; #define LDS_WAIT() asm volatile("s_waitcnt lgkmcnt(0)" ::: "memory")
; __device__ __forceinline__ void select_query(const float* sc, int* sel, int ce, int lane) {
;     const int nreg = ce >> 6;
;     unsigned key[64];
;     {
;         float raw[64];
; #pragma unroll
;         for (int g = 0; g < 8; ++g) {
;             if (8 * g < nreg) {
; #pragma unroll
;                 for (int j = 8 * g; j < 8 * g + 8; ++j) raw[j] = sc[lane + 64 * j];
;             } else {
; #pragma unroll
;                 for (int j = 8 * g; j < 8 * g + 8; ++j) raw[j] = 0.f;
;             }
;         }
; #pragma unroll
;         for (int j = 0; j < 64; ++j) key[j] = (j < nreg) ? fkey(raw[j]) : 0u;
; __device__ __forceinline__ void idx_unit(bf16* QB, float* SC, int* SEL, const float* qg, const float* kg, int b, int tp, LAS unsigned char* wl, int lane, bool do_norm) {
;     ...
;             for (int tt = 0; tt < 2; ++tt) {
;                 f32x16 acc0, acc1;
; #pragma unroll
;                 for (int r = 0; r < 16; ++r) { acc0[r] = 0.f; acc1[r] = 0.f; }
; #pragma unroll
;                 for (int ks = 0; ks < 4; ++ks) { const bf16x8 bfr = *(const LAS bf16x8*)(fsrc + tt * 32 * 144 + 32 * ks);
;                     acc0 = __builtin_amdgcn_mfma_f32_32x32x16_bf16(af[0][ks], bfr, acc0, 0, 0, 0); acc1 = __builtin_amdgcn_mfma_f32_32x32x16_bf16(af[1][ks], bfr, acc1, 0, 0, 0); }
;                 float pa = 0.f, pb = 0.f, pc = 0.f, pd = 0.f;
; #pragma unroll
;                 for (int r = 0; r < 8; ++r) { pa += w[0][r] * (__builtin_fmaxf(acc0[r], 0.f) * 0.125f); pb += w[1][r] * (__builtin_fmaxf(acc0[8 + r], 0.f) * 0.125f);
;                                               pc += w[2][r] * (__builtin_fmaxf(acc1[r], 0.f) * 0.125f); pd += w[3][r] * (__builtin_fmaxf(acc1[8 + r], 0.f) * 0.125f); }
;                 const float snd0 = hi ? pa : pb, snd1 = hi ? pc : pd; const float rcv0 = __shfl_xor(snd0, 32), rcv1 = __shfl_xor(snd1, 32);
;                 scw0[s0 + 32 * tt] = (hi ? pb : pa) + rcv0;
;                 scw1[s0 + 32 * tt] = (hi ? pd : pc) + rcv1;
;             }
;             LDS_WAIT();
;         }
;         __builtin_amdgcn_fence(__ATOMIC_SEQ_CST, "workgroup");
;         asm volatile("s_waitcnt vmcnt(0)" ::: "memory");
; #pragma unroll 1
;         for (int a = 0; a < 4; ++a) select_query(SC + (row + a) * SEQ, SEL + (row + a) * 256, ce, lane);
	v_add_f32_e32 v0, v0, v2
	global_store_dword v[134:135], v1, off
	global_store_dword v[136:137], v0, off
	v_mfma_f32_32x32x16_bf16 v[16:31], v[40:43], v[154:157], 0
	v_mfma_f32_32x32x16_bf16 v[0:15], v[56:59], v[154:157], 0
	v_mfma_f32_32x32x16_bf16 v[0:15], v[48:51], v[158:161], v[0:15]
	v_mfma_f32_32x32x16_bf16 v[16:31], v[32:35], v[158:161], v[16:31]
	v_mfma_f32_32x32x16_bf16 v[0:15], v[52:55], v[162:165], v[0:15]
	v_mfma_f32_32x32x16_bf16 v[16:31], v[36:39], v[162:165], v[16:31]
	v_mfma_f32_32x32x16_bf16 v[0:15], v[60:63], v[166:169], v[0:15]
	v_mfma_f32_32x32x16_bf16 v[16:31], v[44:47], v[166:169], v[16:31]
	s_nop 10
	v_max_f32_e32 v0, 0, v0
	v_max_f32_e32 v1, 0, v1
	v_fma_f32 v0, v232, v0, 0
	v_max_f32_e32 v8, 0, v8
	v_fmac_f32_e32 v0, v233, v1
	v_max_f32_e32 v1, 0, v9
	v_max_f32_e32 v16, 0, v16
	v_fma_f32 v8, v240, v8, 0
	v_max_f32_e32 v17, 0, v17
	v_fmac_f32_e32 v8, v241, v1
	v_fma_f32 v16, v131, v16, 0
	v_max_f32_e32 v1, 0, v18
	v_max_f32_e32 v24, 0, v24
	v_fmac_f32_e32 v16, v217, v17
	v_max_f32_e32 v17, 0, v25
	v_fmac_f32_e32 v16, v218, v1
	v_fma_f32 v24, v224, v24, 0
	v_max_f32_e32 v1, 0, v26
	v_fmac_f32_e32 v24, v225, v17
	v_fmac_f32_e32 v24, v226, v1
	v_max_f32_e32 v1, 0, v2
	v_fmac_f32_e32 v0, v234, v1
	v_max_f32_e32 v1, 0, v10
	v_fmac_f32_e32 v8, v242, v1
	v_max_f32_e32 v1, 0, v19
	v_fmac_f32_e32 v16, v219, v1
	v_max_f32_e32 v1, 0, v27
	v_fmac_f32_e32 v24, v227, v1
	v_max_f32_e32 v1, 0, v3
	v_fmac_f32_e32 v0, v235, v1
	v_max_f32_e32 v1, 0, v11
	v_fmac_f32_e32 v8, v243, v1
	v_max_f32_e32 v1, 0, v20
	v_fmac_f32_e32 v16, v220, v1
	v_max_f32_e32 v1, 0, v28
	v_fmac_f32_e32 v24, v228, v1
	v_max_f32_e32 v1, 0, v4
	v_fmac_f32_e32 v0, v236, v1
	v_max_f32_e32 v1, 0, v12
	v_fmac_f32_e32 v8, v244, v1
	v_max_f32_e32 v1, 0, v21
	v_fmac_f32_e32 v16, v221, v1
	v_max_f32_e32 v1, 0, v29
	v_fmac_f32_e32 v24, v229, v1
	v_max_f32_e32 v1, 0, v5
	v_fmac_f32_e32 v0, v237, v1
	v_max_f32_e32 v1, 0, v13
	v_fmac_f32_e32 v8, v245, v1
	v_max_f32_e32 v1, 0, v22
	v_fmac_f32_e32 v16, v222, v1
	v_max_f32_e32 v1, 0, v30
	v_fmac_f32_e32 v24, v230, v1
	v_max_f32_e32 v1, 0, v6
	v_fmac_f32_e32 v0, v238, v1
	v_max_f32_e32 v1, 0, v14
	v_fmac_f32_e32 v8, v246, v1
	v_max_f32_e32 v1, 0, v23
	v_fmac_f32_e32 v16, v223, v1
	v_max_f32_e32 v1, 0, v31
	v_fmac_f32_e32 v24, v231, v1
	v_max_f32_e32 v1, 0, v7
	v_fmac_f32_e32 v0, v239, v1
	v_max_f32_e32 v1, 0, v15
	v_fmac_f32_e32 v8, v247, v1
	v_cndmask_b32_e64 v1, v16, v24, s[40:41]
	v_cndmask_b32_e64 v2, v0, v8, s[40:41]
	ds_bpermute_b32 v1, v97, v1
	ds_bpermute_b32 v2, v97, v2
	v_cndmask_b32_e64 v3, v24, v16, s[40:41]
	v_cndmask_b32_e64 v0, v8, v0, s[40:41]
	s_waitcnt lgkmcnt(1)
	v_add_f32_e32 v1, v3, v1
	s_waitcnt lgkmcnt(0)
	v_add_f32_e32 v0, v0, v2
	global_store_dword v[134:135], v1, off offset:128
	global_store_dword v[136:137], v0, off offset:128
	s_waitcnt lgkmcnt(0)
	v_lshl_add_u64 v[134:135], v[134:135], 0, s[0:1]
	s_mov_b32 s0, s3
	s_cbranch_vccnz .LBB0_243
	v_add_u32_e32 v138, 0x180, v96
	v_add_u32_e32 v139, 0x1c0, v96
	v_add_u32_e32 v140, 0x200, v96
	v_add_u32_e32 v141, 0x240, v96
	v_add_u32_e32 v142, 0x280, v96
	v_add_u32_e32 v143, 0x2c0, v96
	v_add_u32_e32 v144, 0x300, v96
	v_add_u32_e32 v145, 0x340, v96
	v_add_u32_e32 v146, 0x380, v96
	v_add_u32_e32 v147, 0x3c0, v96
	v_add_u32_e32 v148, 0x400, v96
	v_add_u32_e32 v149, 0x440, v96
	v_add_u32_e32 v150, 0x480, v96
	v_add_u32_e32 v151, 0x4c0, v96
	v_add_u32_e32 v152, 0x500, v96
	v_add_u32_e32 v153, 0x540, v96
	v_add_u32_e32 v154, 0x580, v96
	v_add_u32_e32 v155, 0x5c0, v96
	v_add_u32_e32 v156, 0x600, v96
	v_add_u32_e32 v157, 0x640, v96
	v_add_u32_e32 v158, 0x680, v96
	v_add_u32_e32 v159, 0x6c0, v96
	v_add_u32_e32 v160, 0x700, v96
	v_add_u32_e32 v161, 0x740, v96
	v_add_u32_e32 v162, 0x780, v96
	v_add_u32_e32 v163, 0x7c0, v96
	v_add_u32_e32 v164, 0x800, v96
	v_add_u32_e32 v165, 0x840, v96
	v_add_u32_e32 v166, 0x880, v96
	v_add_u32_e32 v167, 0x8c0, v96
	v_add_u32_e32 v168, 0x900, v96
	v_add_u32_e32 v169, 0x940, v96
	s_cmpk_gt_u32 s6, 0x23f
	s_cselect_b64 s[84:85], -1, 0
	s_cmpk_gt_u32 s6, 0x43f
	s_cselect_b64 s[86:87], -1, 0
	s_cmpk_gt_u32 s6, 0x63f
	s_cselect_b64 s[88:89], -1, 0
	s_cmpk_gt_u32 s6, 0x83f
	s_cselect_b64 s[90:91], -1, 0
	s_cmpk_gt_u32 s6, 0xa3f
	s_cselect_b64 s[92:93], -1, 0
	s_cmpk_gt_u32 s6, 0xc3f
	s_cselect_b64 s[94:95], -1, 0
	s_cmpk_gt_u32 s6, 0xe3f
	s_cselect_b64 s[96:97], -1, 0
	s_cmpk_gt_u32 s6, 0x17f
	s_cselect_b64 s[0:1], -1, 0
	v_writelane_b32 v254, s0, 7
	s_cmpk_gt_u32 s6, 0x1bf
	s_nop 0
	v_writelane_b32 v254, s1, 8
	s_cselect_b64 s[0:1], -1, 0
	v_writelane_b32 v254, s0, 9
	s_cmpk_gt_u32 s6, 0x1ff
	s_waitcnt vmcnt(0)
; __device__ __forceinline__ unsigned fkey(float f) { const unsigned u = __builtin_bit_cast(unsigned, f); return (u & 0x80000000u) ? ~u : (u | 0x80000000u); }
; __device__ __forceinline__ void select_query(const float* sc, int* sel, int ce, int lane) {
;     const int nreg = ce >> 6;
;     unsigned key[64];
;     {
;         float raw[64];
; #pragma unroll
;         for (int g = 0; g < 8; ++g) {
;             if (8 * g < nreg) {
; #pragma unroll
;                 for (int j = 8 * g; j < 8 * g + 8; ++j) raw[j] = sc[lane + 64 * j];
;             } else {
; #pragma unroll
;                 for (int j = 8 * g; j < 8 * g + 8; ++j) raw[j] = 0.f;
;             }
;         }
; #pragma unroll
;         for (int j = 0; j < 64; ++j) key[j] = (j < nreg) ? fkey(raw[j]) : 0u;
	s_mov_b32 s3, 0
	v_writelane_b32 v254, s1, 10
	s_cselect_b64 s[0:1], -1, 0
	v_writelane_b32 v254, s0, 11
	s_cmpk_gt_u32 s6, 0x27f
	s_nop 0
	v_writelane_b32 v254, s1, 12
	s_cselect_b64 s[0:1], -1, 0
	v_writelane_b32 v254, s0, 13
	s_cmpk_gt_u32 s6, 0x2bf
	s_nop 0
	v_writelane_b32 v254, s1, 14
	s_cselect_b64 s[0:1], -1, 0
	v_writelane_b32 v254, s0, 15
	s_cmpk_gt_u32 s6, 0x2ff
	s_nop 0
	v_writelane_b32 v254, s1, 16
	s_cselect_b64 s[0:1], -1, 0
	v_writelane_b32 v254, s0, 17
	s_cmpk_gt_u32 s6, 0x33f
	s_nop 0
	v_writelane_b32 v254, s1, 18
	s_cselect_b64 s[0:1], -1, 0
	v_writelane_b32 v254, s0, 19
	s_cmpk_gt_u32 s6, 0x37f
	s_nop 0
	v_writelane_b32 v254, s1, 20
	s_cselect_b64 s[0:1], -1, 0
	v_writelane_b32 v254, s0, 21
	s_cmpk_gt_u32 s6, 0x3bf
	s_nop 0
	v_writelane_b32 v254, s1, 22
	s_cselect_b64 s[0:1], -1, 0
	v_writelane_b32 v254, s0, 23
	s_cmpk_gt_u32 s6, 0x3ff
	s_nop 0
	v_writelane_b32 v254, s1, 24
	s_cselect_b64 s[0:1], -1, 0
	v_writelane_b32 v254, s0, 25
	s_cmpk_gt_u32 s6, 0x47f
	s_nop 0
	v_writelane_b32 v254, s1, 26
	s_cselect_b64 s[0:1], -1, 0
	v_writelane_b32 v254, s0, 27
	s_cmpk_gt_u32 s6, 0x4bf
	s_nop 0
	v_writelane_b32 v254, s1, 28
	s_cselect_b64 s[0:1], -1, 0
	v_writelane_b32 v254, s0, 29
	s_cmpk_gt_u32 s6, 0x4ff
	s_nop 0
	v_writelane_b32 v254, s1, 30
	s_cselect_b64 s[0:1], -1, 0
	v_writelane_b32 v254, s0, 31
	s_cmpk_gt_u32 s6, 0x53f
	s_nop 0
	v_writelane_b32 v254, s1, 32
	s_cselect_b64 s[0:1], -1, 0
	v_writelane_b32 v254, s0, 33
	s_cmpk_gt_u32 s6, 0x57f
	s_nop 0
	v_writelane_b32 v254, s1, 34
	s_cselect_b64 s[0:1], -1, 0
	v_writelane_b32 v254, s0, 35
	s_cmpk_gt_u32 s6, 0x5bf
	s_nop 0
	v_writelane_b32 v254, s1, 36
	s_cselect_b64 s[0:1], -1, 0
	v_writelane_b32 v254, s0, 37
	s_cmpk_gt_u32 s6, 0x5ff
	s_nop 0
	v_writelane_b32 v254, s1, 38
	s_cselect_b64 s[0:1], -1, 0
	v_writelane_b32 v254, s0, 39
	s_cmpk_gt_u32 s6, 0x67f
	s_nop 0
	v_writelane_b32 v254, s1, 40
	s_cselect_b64 s[0:1], -1, 0
	v_writelane_b32 v254, s0, 41
	s_cmpk_gt_u32 s6, 0x6bf
	s_nop 0
	v_writelane_b32 v254, s1, 42
	s_cselect_b64 s[0:1], -1, 0
	v_writelane_b32 v254, s0, 43
	s_cmpk_gt_u32 s6, 0x6ff
	s_nop 0
	v_writelane_b32 v254, s1, 44
	s_cselect_b64 s[0:1], -1, 0
	v_writelane_b32 v254, s0, 45
	s_cmpk_gt_u32 s6, 0x73f
	s_nop 0
	v_writelane_b32 v254, s1, 46
	s_cselect_b64 s[0:1], -1, 0
	v_writelane_b32 v254, s0, 47
	s_cmpk_gt_u32 s6, 0x77f
	s_nop 0
	v_writelane_b32 v254, s1, 48
	s_cselect_b64 s[0:1], -1, 0
	v_writelane_b32 v254, s0, 49
	s_cmpk_gt_u32 s6, 0x7bf
	s_nop 0
	v_writelane_b32 v254, s1, 50
	s_cselect_b64 s[0:1], -1, 0
	v_writelane_b32 v254, s0, 51
	s_cmpk_gt_u32 s6, 0x7ff
	s_nop 0
	v_writelane_b32 v254, s1, 52
	s_cselect_b64 s[0:1], -1, 0
	v_writelane_b32 v254, s0, 53
	s_cmpk_gt_u32 s6, 0x87f
	s_nop 0
	v_writelane_b32 v254, s1, 54
	s_cselect_b64 s[0:1], -1, 0
	v_writelane_b32 v254, s0, 55
	s_cmpk_gt_u32 s6, 0x8bf
	s_nop 0
	v_writelane_b32 v254, s1, 56
	s_cselect_b64 s[0:1], -1, 0
	v_writelane_b32 v254, s0, 57
	s_cmpk_gt_u32 s6, 0x8ff
	s_nop 0
	v_writelane_b32 v254, s1, 58
	s_cselect_b64 s[0:1], -1, 0
	v_writelane_b32 v254, s0, 59
	s_cmpk_gt_u32 s6, 0x93f
	s_nop 0
	v_writelane_b32 v254, s1, 60
	s_cselect_b64 s[0:1], -1, 0
	v_writelane_b32 v254, s0, 61
	s_cmpk_gt_u32 s6, 0x97f
	s_nop 0
	v_writelane_b32 v254, s1, 62
	s_cselect_b64 s[0:1], -1, 0
	v_writelane_b32 v254, s0, 63
	s_cmpk_gt_u32 s6, 0x9bf
	s_nop 0
	v_writelane_b32 v250, s1, 0
	s_cselect_b64 s[0:1], -1, 0
	v_writelane_b32 v250, s0, 1
	s_cmpk_gt_u32 s6, 0x9ff
	s_nop 0
	v_writelane_b32 v250, s1, 2
	s_cselect_b64 s[0:1], -1, 0
	v_writelane_b32 v250, s0, 3
	s_cmpk_gt_u32 s6, 0xa7f
	s_nop 0
	v_writelane_b32 v250, s1, 4
	s_cselect_b64 s[0:1], -1, 0
	v_writelane_b32 v250, s0, 5
	s_cmpk_gt_u32 s6, 0xabf
	s_nop 0
	v_writelane_b32 v250, s1, 6
	s_cselect_b64 s[0:1], -1, 0
	v_writelane_b32 v250, s0, 7
	s_cmpk_gt_u32 s6, 0xaff
	s_nop 0
	v_writelane_b32 v250, s1, 8
	s_cselect_b64 s[0:1], -1, 0
	v_writelane_b32 v250, s0, 9
	s_cmpk_gt_u32 s6, 0xb3f
	s_nop 0
	v_writelane_b32 v250, s1, 10
	s_cselect_b64 s[0:1], -1, 0
	v_writelane_b32 v250, s0, 11
	s_cmpk_gt_u32 s6, 0xb7f
	s_nop 0
	v_writelane_b32 v250, s1, 12
	s_cselect_b64 s[0:1], -1, 0
	v_writelane_b32 v250, s0, 13
	s_cmpk_gt_u32 s6, 0xbbf
	s_nop 0
	v_writelane_b32 v250, s1, 14
	s_cselect_b64 s[0:1], -1, 0
	v_writelane_b32 v250, s0, 15
	s_cmpk_gt_u32 s6, 0xbff
	s_nop 0
	v_writelane_b32 v250, s1, 16
	s_cselect_b64 s[0:1], -1, 0
	v_writelane_b32 v250, s0, 17
	s_cmpk_gt_u32 s6, 0xc7f
	s_nop 0
	v_writelane_b32 v250, s1, 18
	s_cselect_b64 s[0:1], -1, 0
	v_writelane_b32 v250, s0, 19
	s_cmpk_gt_u32 s6, 0xcbf
	s_nop 0
	v_writelane_b32 v250, s1, 20
	s_cselect_b64 s[0:1], -1, 0
	v_writelane_b32 v250, s0, 21
	s_cmpk_gt_u32 s6, 0xcff
	s_nop 0
	v_writelane_b32 v250, s1, 22
	s_cselect_b64 s[0:1], -1, 0
	v_writelane_b32 v250, s0, 23
	s_cmpk_gt_u32 s6, 0xd3f
	s_nop 0
	v_writelane_b32 v250, s1, 24
	s_cselect_b64 s[0:1], -1, 0
	v_writelane_b32 v250, s0, 25
	s_cmpk_gt_u32 s6, 0xd7f
	s_nop 0
	v_writelane_b32 v250, s1, 26
	s_cselect_b64 s[0:1], -1, 0
	v_writelane_b32 v250, s0, 27
	s_cmpk_gt_u32 s6, 0xdbf
	s_nop 0
	v_writelane_b32 v250, s1, 28
	s_cselect_b64 s[0:1], -1, 0
	v_writelane_b32 v250, s0, 29
	s_cmpk_gt_u32 s6, 0xdff
	s_nop 0
	v_writelane_b32 v250, s1, 30
	s_cselect_b64 s[0:1], -1, 0
	s_cmpk_gt_u32 s6, 0xe7f
	s_cselect_b64 s[36:37], -1, 0
	s_cmpk_gt_u32 s6, 0xebf
	s_cselect_b64 s[38:39], -1, 0
	s_cmpk_gt_u32 s6, 0xeff
	s_cselect_b64 s[42:43], -1, 0
	s_cmpk_gt_u32 s6, 0xf3f
	s_cselect_b64 s[44:45], -1, 0
	s_cmpk_gt_u32 s6, 0xf7f
	s_cselect_b64 s[46:47], -1, 0
	s_cmpk_gt_u32 s6, 0xfbf
	s_cselect_b64 s[48:49], -1, 0
	s_cmpk_gt_u32 s6, 0xfff
	v_writelane_b32 v250, s0, 31
	s_cselect_b64 s[50:51], -1, 0
	s_nop 0
	v_writelane_b32 v250, s1, 32
	s_branch .LBB0_247
